# nt (non-temporal) on the P1a/P1b/P5 GEMM epilogue stores so large write-once outputs do not displace GEMM operands from cache
# baseline (speedup 1.0000x reference)
; __device__ __forceinline__ unsigned cvt_pk_bf16(float lo, float hi) { unsigned r; asm volatile("v_cvt_pk_bf16_f32 %0, %1, %2" : "=v"(r) : "v"(lo), "v"(hi)); return r; }
; #define PG8_BAR __builtin_amdgcn_s_barrier()
;     __device__ __forceinline__ void operator()(const f32x4 (&acc)[2][2][4][2], const Unit& u, int wr, int wc, int fr, int fq) const {
;     ...
;         for (int ai = 0; ai < 2; ++ai)
; #pragma unroll
;             for (int m = 0; m < 4; ++m) { bf16_t* rowp = O + (size_t)(row0 + ai * HALF + m * 16) * ldc + col0;
; #pragma unroll
;                 for (int bj = 0; bj < 2; ++bj) { const f32x4 v0 = acc[ai][bj][m][0], v1 = acc[ai][bj][m][1];
;                     u32x4 w; w.x = cvt_pk_bf16(v0[0], v0[1]); w.y = cvt_pk_bf16(v0[2], v0[3]); w.z = cvt_pk_bf16(v1[0], v1[1]); w.w = cvt_pk_bf16(v1[2], v1[3]);
;                     *(u32x4*)(rowp + bj * HALF) = w; } }
; template <class Epi, class Sched, bool ALIGN_EPI = false, bool SP2 = false>
; __device__ __forceinline__ void gemm_phase(PG8_LAS unsigned char* lds, const Gemm g, const Sched& S, const Epi& E) {
;     ...
;         if constexpr (ALIGN_EPI) { if (wr == 0) PG8_BAR; }
;         if constexpr (!Epi::AFTER_DRAIN) { E(acc, cur, wr, wc, fr, fq); S.done(cur); }
;         if (!has_next) break;
; #pragma unroll
;         for (int a = 0; a < 2; ++a)
; #pragma unroll
;             for (int b = 0; b < 2; ++b)
; #pragma unroll
;                 for (int m = 0; m < 4; ++m)
; #pragma unroll
;                     for (int n = 0; n < 2; ++n) acc[a][b][m][n] = (f32x4){0.f, 0.f, 0.f, 0.f};
;         cur = nxt; cA = nA; cB = nB; ++ui;
;         if constexpr (ALIGN_EPI) { if (wr == 1) PG8_BAR; }
.LBB0_142:
	v_lshl_or_b32 v146, s79, 8, v159
	v_lshl_add_u32 v163, s28, 8, v157
	v_ashrrev_i32_e32 v147, 31, v146
	v_mov_b64_e32 v[144:145], s[70:71]
	v_mad_i64_i32 v[164:165], s[30:31], v163, s78, v[144:145]
	v_lshlrev_b64 v[146:147], 1, v[146:147]
	v_lshl_add_u64 v[164:165], v[164:165], 0, v[146:147]
	v_cvt_pk_bf16_f32 v124, v124, v125
	v_cvt_pk_bf16_f32 v125, v126, v127
	v_cvt_pk_bf16_f32 v126, v120, v121
	v_cvt_pk_bf16_f32 v127, v122, v123
	global_store_dwordx4 v[164:165], v[124:127], off nt
	v_cvt_pk_bf16_f32 v112, v112, v113
	v_cvt_pk_bf16_f32 v113, v114, v115
	v_cvt_pk_bf16_f32 v114, v104, v105
	v_or_b32_e32 v104, 16, v163
	v_mad_i64_i32 v[104:105], s[30:31], v104, s78, v[144:145]
	v_cvt_pk_bf16_f32 v115, v106, v107
	global_store_dwordx4 v[164:165], v[112:115], off offset:256 nt
	s_andn2_b64 vcc, exec, s[6:7]
	s_mov_b64 s[6:7], -1
	v_lshl_add_u64 v[112:113], v[104:105], 0, v[146:147]
	v_cvt_pk_bf16_f32 v104, v116, v117
	v_cvt_pk_bf16_f32 v105, v118, v119
	v_cvt_pk_bf16_f32 v106, v108, v109
	v_cvt_pk_bf16_f32 v107, v110, v111
	global_store_dwordx4 v[112:113], v[104:107], off nt
	v_cvt_pk_bf16_f32 v96, v96, v97
	v_cvt_pk_bf16_f32 v97, v98, v99
	v_cvt_pk_bf16_f32 v98, v88, v89
	v_or_b32_e32 v88, 32, v163
	v_mad_i64_i32 v[88:89], s[30:31], v88, s78, v[144:145]
	v_cvt_pk_bf16_f32 v99, v90, v91
	global_store_dwordx4 v[112:113], v[96:99], off offset:256 nt
	s_nop 1
	v_lshl_add_u64 v[96:97], v[88:89], 0, v[146:147]
	v_cvt_pk_bf16_f32 v88, v100, v101
	v_cvt_pk_bf16_f32 v89, v102, v103
	v_cvt_pk_bf16_f32 v90, v92, v93
	v_cvt_pk_bf16_f32 v91, v94, v95
	global_store_dwordx4 v[96:97], v[88:91], off nt
	v_cvt_pk_bf16_f32 v80, v80, v81
	v_cvt_pk_bf16_f32 v81, v82, v83
	v_cvt_pk_bf16_f32 v82, v72, v73
	v_or_b32_e32 v72, 48, v163
	v_mad_i64_i32 v[72:73], s[30:31], v72, s78, v[144:145]
	v_cvt_pk_bf16_f32 v83, v74, v75
	global_store_dwordx4 v[96:97], v[80:83], off offset:256 nt
	s_nop 1
	v_lshl_add_u64 v[80:81], v[72:73], 0, v[146:147]
	v_cvt_pk_bf16_f32 v72, v84, v85
	v_cvt_pk_bf16_f32 v73, v86, v87
	v_cvt_pk_bf16_f32 v74, v76, v77
	v_cvt_pk_bf16_f32 v75, v78, v79
	global_store_dwordx4 v[80:81], v[72:75], off nt
	v_cvt_pk_bf16_f32 v68, v68, v69
	v_cvt_pk_bf16_f32 v69, v70, v71
	v_cvt_pk_bf16_f32 v70, v64, v65
	v_add_u32_e32 v64, 0x80, v163
	v_mad_i64_i32 v[64:65], s[30:31], v64, s78, v[144:145]
	v_lshl_add_u64 v[64:65], v[64:65], 0, v[146:147]
	v_cvt_pk_bf16_f32 v71, v66, v67
	global_store_dwordx4 v[80:81], v[68:71], off offset:256 nt
	v_cvt_pk_bf16_f32 v60, v60, v61
	v_cvt_pk_bf16_f32 v61, v62, v63
	v_cvt_pk_bf16_f32 v62, v56, v57
	v_cvt_pk_bf16_f32 v63, v58, v59
	global_store_dwordx4 v[64:65], v[60:63], off nt
	v_cvt_pk_bf16_f32 v48, v48, v49
	v_cvt_pk_bf16_f32 v49, v50, v51
	v_cvt_pk_bf16_f32 v50, v40, v41
	v_add_u32_e32 v40, 0x90, v163
	v_mad_i64_i32 v[40:41], s[30:31], v40, s78, v[144:145]
	v_cvt_pk_bf16_f32 v51, v42, v43
	global_store_dwordx4 v[64:65], v[48:51], off offset:256 nt
	s_nop 1
	v_lshl_add_u64 v[48:49], v[40:41], 0, v[146:147]
	v_cvt_pk_bf16_f32 v40, v52, v53
	v_cvt_pk_bf16_f32 v41, v54, v55
	v_cvt_pk_bf16_f32 v42, v44, v45
	v_cvt_pk_bf16_f32 v43, v46, v47
	global_store_dwordx4 v[48:49], v[40:43], off nt
	v_cvt_pk_bf16_f32 v32, v32, v33
	v_cvt_pk_bf16_f32 v33, v34, v35
	v_cvt_pk_bf16_f32 v34, v24, v25
	v_add_u32_e32 v24, 0xa0, v163
	v_mad_i64_i32 v[24:25], s[30:31], v24, s78, v[144:145]
	v_cvt_pk_bf16_f32 v35, v26, v27
	global_store_dwordx4 v[48:49], v[32:35], off offset:256 nt
	s_nop 1
	v_lshl_add_u64 v[32:33], v[24:25], 0, v[146:147]
	v_cvt_pk_bf16_f32 v24, v36, v37
	v_cvt_pk_bf16_f32 v25, v38, v39
	v_cvt_pk_bf16_f32 v26, v28, v29
	v_cvt_pk_bf16_f32 v27, v30, v31
	global_store_dwordx4 v[32:33], v[24:27], off nt
	v_cvt_pk_bf16_f32 v16, v16, v17
	v_cvt_pk_bf16_f32 v17, v18, v19
	v_cvt_pk_bf16_f32 v18, v8, v9
	v_add_u32_e32 v8, 0xb0, v163
	v_mad_i64_i32 v[8:9], s[30:31], v8, s78, v[144:145]
	v_cvt_pk_bf16_f32 v19, v10, v11
	global_store_dwordx4 v[32:33], v[16:19], off offset:256 nt
	s_nop 1
	v_lshl_add_u64 v[16:17], v[8:9], 0, v[146:147]
	v_cvt_pk_bf16_f32 v8, v20, v21
	v_cvt_pk_bf16_f32 v9, v22, v23
	v_cvt_pk_bf16_f32 v10, v12, v13
	v_cvt_pk_bf16_f32 v11, v14, v15
	global_store_dwordx4 v[16:17], v[8:11], off nt
	v_cvt_pk_bf16_f32 v4, v4, v5
	v_cvt_pk_bf16_f32 v5, v6, v7
	v_cvt_pk_bf16_f32 v6, v0, v1
	v_cvt_pk_bf16_f32 v7, v2, v3
	global_store_dwordx4 v[16:17], v[4:7], off offset:256 nt
	s_cbranch_vccnz .LBB0_135
	s_andn2_b64 vcc, exec, s[10:11]
	s_cbranch_vccnz .LBB0_134
	s_barrier
	s_branch .LBB0_134

; __device__ __forceinline__ unsigned cvt_pk_bf16(float lo, float hi) { unsigned r; asm volatile("v_cvt_pk_bf16_f32 %0, %1, %2" : "=v"(r) : "v"(lo), "v"(hi)); return r; }
; #define PG8_BAR __builtin_amdgcn_s_barrier()
;     __device__ __forceinline__ void operator()(const f32x4 (&acc)[2][2][4][2], const Unit& u, int wr, int wc, int fr, int fq) const {
;     ...
;         for (int ai = 0; ai < 2; ++ai)
; #pragma unroll
;             for (int m = 0; m < 4; ++m) { bf16_t* rowp = O + (size_t)(row0 + ai * HALF + m * 16) * ldc + col0;
; #pragma unroll
;                 for (int bj = 0; bj < 2; ++bj) { const f32x4 v0 = acc[ai][bj][m][0], v1 = acc[ai][bj][m][1];
;                     u32x4 w; w.x = cvt_pk_bf16(v0[0], v0[1]); w.y = cvt_pk_bf16(v0[2], v0[3]); w.z = cvt_pk_bf16(v1[0], v1[1]); w.w = cvt_pk_bf16(v1[2], v1[3]);
;                     *(u32x4*)(rowp + bj * HALF) = w; } }
; template <class Epi, class Sched, bool ALIGN_EPI = false, bool SP2 = false>
; __device__ __forceinline__ void gemm_phase(PG8_LAS unsigned char* lds, const Gemm g, const Sched& S, const Epi& E) {
;     ...
;         if constexpr (ALIGN_EPI) { if (wr == 0) PG8_BAR; }
;         if constexpr (!Epi::AFTER_DRAIN) { E(acc, cur, wr, wc, fr, fq); S.done(cur); }
;         if (!has_next) break;
; #pragma unroll
;         for (int a = 0; a < 2; ++a)
; #pragma unroll
;             for (int b = 0; b < 2; ++b)
; #pragma unroll
;                 for (int m = 0; m < 4; ++m)
; #pragma unroll
;                     for (int n = 0; n < 2; ++n) acc[a][b][m][n] = (f32x4){0.f, 0.f, 0.f, 0.f};
;         cur = nxt; cA = nA; cB = nB; ++ui;
;         if constexpr (ALIGN_EPI) { if (wr == 1) PG8_BAR; }
.LBB0_166:
	v_lshl_add_u32 v148, s28, 8, v142
	v_lshl_or_b32 v140, s89, 8, v144
	v_ashrrev_i32_e32 v149, 31, v148
	v_ashrrev_i32_e32 v141, 31, v140
	v_lshlrev_b64 v[150:151], 12, v[148:149]
	v_lshl_add_u64 v[150:151], s[62:63], 0, v[150:151]
	v_lshlrev_b64 v[152:153], 1, v[140:141]
	v_lshl_add_u64 v[140:141], v[150:151], 0, v[152:153]
	v_cvt_pk_bf16_f32 v124, v124, v125
	v_cvt_pk_bf16_f32 v125, v126, v127
	v_cvt_pk_bf16_f32 v126, v120, v121
	v_cvt_pk_bf16_f32 v127, v122, v123
	global_store_dwordx4 v[140:141], v[124:127], off nt
	v_cvt_pk_bf16_f32 v112, v112, v113
	v_cvt_pk_bf16_f32 v113, v114, v115
	v_cvt_pk_bf16_f32 v114, v104, v105
	v_or_b32_e32 v104, 16, v148
	v_ashrrev_i32_e32 v105, 31, v104
	v_lshlrev_b64 v[104:105], 12, v[104:105]
	v_lshl_add_u64 v[104:105], s[62:63], 0, v[104:105]
	v_cvt_pk_bf16_f32 v115, v106, v107
	global_store_dwordx4 v[140:141], v[112:115], off offset:256 nt
	s_mov_b32 s21, 0x80000
	s_mov_b64 s[28:29], 0x80000
	v_lshl_add_u64 v[112:113], v[104:105], 0, v[152:153]
	v_cvt_pk_bf16_f32 v104, v116, v117
	v_cvt_pk_bf16_f32 v105, v118, v119
	v_cvt_pk_bf16_f32 v106, v108, v109
	v_cvt_pk_bf16_f32 v107, v110, v111
	global_store_dwordx4 v[112:113], v[104:107], off nt
	v_cvt_pk_bf16_f32 v96, v96, v97
	v_cvt_pk_bf16_f32 v97, v98, v99
	v_cvt_pk_bf16_f32 v98, v88, v89
	v_or_b32_e32 v88, 32, v148
	v_ashrrev_i32_e32 v89, 31, v88
	v_lshlrev_b64 v[88:89], 12, v[88:89]
	v_lshl_add_u64 v[88:89], s[62:63], 0, v[88:89]
	v_cvt_pk_bf16_f32 v99, v90, v91
	global_store_dwordx4 v[112:113], v[96:99], off offset:256 nt
	s_nop 1
	v_lshl_add_u64 v[96:97], v[88:89], 0, v[152:153]
	v_cvt_pk_bf16_f32 v88, v100, v101
	v_cvt_pk_bf16_f32 v89, v102, v103
	v_cvt_pk_bf16_f32 v90, v92, v93
	v_cvt_pk_bf16_f32 v91, v94, v95
	global_store_dwordx4 v[96:97], v[88:91], off nt
	v_cvt_pk_bf16_f32 v80, v80, v81
	v_cvt_pk_bf16_f32 v81, v82, v83
	v_cvt_pk_bf16_f32 v82, v72, v73
	v_or_b32_e32 v72, 48, v148
	v_ashrrev_i32_e32 v73, 31, v72
	v_lshlrev_b64 v[72:73], 12, v[72:73]
	v_lshl_add_u64 v[72:73], s[62:63], 0, v[72:73]
	v_cvt_pk_bf16_f32 v83, v74, v75
	global_store_dwordx4 v[96:97], v[80:83], off offset:256 nt
	s_nop 1
	v_lshl_add_u64 v[80:81], v[72:73], 0, v[152:153]
	v_cvt_pk_bf16_f32 v72, v84, v85
	v_cvt_pk_bf16_f32 v73, v86, v87
	v_cvt_pk_bf16_f32 v74, v76, v77
	v_cvt_pk_bf16_f32 v75, v78, v79
	global_store_dwordx4 v[80:81], v[72:75], off nt
	v_cvt_pk_bf16_f32 v68, v68, v69
	v_cvt_pk_bf16_f32 v69, v70, v71
	v_cvt_pk_bf16_f32 v70, v64, v65
	v_cvt_pk_bf16_f32 v71, v66, v67
	global_store_dwordx4 v[80:81], v[68:71], off offset:256 nt
	v_cvt_pk_bf16_f32 v60, v60, v61
	v_cvt_pk_bf16_f32 v61, v62, v63
	v_cvt_pk_bf16_f32 v62, v56, v57
	v_add_co_u32_e32 v56, vcc, s21, v140
	v_lshl_add_u64 v[64:65], v[140:141], 0, s[28:29]
	s_nop 0
	v_addc_co_u32_e32 v57, vcc, 0, v141, vcc
	s_mov_b32 s21, 0x90000
	v_cvt_pk_bf16_f32 v63, v58, v59
	global_store_dwordx4 v[56:57], v[60:63], off nt
	v_cvt_pk_bf16_f32 v48, v48, v49
	v_cvt_pk_bf16_f32 v49, v50, v51
	v_cvt_pk_bf16_f32 v50, v40, v41
	v_cvt_pk_bf16_f32 v51, v42, v43
	global_store_dwordx4 v[64:65], v[48:51], off offset:256 nt
	s_mov_b64 s[28:29], 0x90000
	v_cvt_pk_bf16_f32 v40, v52, v53
	v_cvt_pk_bf16_f32 v41, v54, v55
	v_cvt_pk_bf16_f32 v42, v44, v45
	v_add_co_u32_e32 v44, vcc, s21, v140
	v_lshl_add_u64 v[48:49], v[140:141], 0, s[28:29]
	s_nop 0
	v_addc_co_u32_e32 v45, vcc, 0, v141, vcc
	s_mov_b32 s21, 0xa0000
	v_cvt_pk_bf16_f32 v43, v46, v47
	global_store_dwordx4 v[44:45], v[40:43], off nt
	v_cvt_pk_bf16_f32 v32, v32, v33
	v_cvt_pk_bf16_f32 v33, v34, v35
	v_cvt_pk_bf16_f32 v34, v24, v25
	v_cvt_pk_bf16_f32 v35, v26, v27
	global_store_dwordx4 v[48:49], v[32:35], off offset:256 nt
	s_mov_b64 s[28:29], 0xa0000
	v_cvt_pk_bf16_f32 v24, v36, v37
	v_cvt_pk_bf16_f32 v25, v38, v39
	v_cvt_pk_bf16_f32 v26, v28, v29
	v_add_co_u32_e32 v28, vcc, s21, v140
	v_lshl_add_u64 v[32:33], v[140:141], 0, s[28:29]
	s_nop 0
	v_addc_co_u32_e32 v29, vcc, 0, v141, vcc
	s_mov_b32 s21, 0xb0000
	v_cvt_pk_bf16_f32 v27, v30, v31
	global_store_dwordx4 v[28:29], v[24:27], off nt
	v_cvt_pk_bf16_f32 v16, v16, v17
	v_cvt_pk_bf16_f32 v17, v18, v19
	v_cvt_pk_bf16_f32 v18, v8, v9
	v_cvt_pk_bf16_f32 v19, v10, v11
	global_store_dwordx4 v[32:33], v[16:19], off offset:256 nt
	v_cvt_pk_bf16_f32 v8, v20, v21
	v_cvt_pk_bf16_f32 v9, v22, v23
	v_cvt_pk_bf16_f32 v10, v12, v13
	v_add_co_u32_e32 v12, vcc, s21, v140
	s_mov_b64 s[28:29], 0xb0000
	s_nop 0
	v_addc_co_u32_e32 v13, vcc, 0, v141, vcc
	v_lshl_add_u64 v[16:17], v[140:141], 0, s[28:29]
	s_andn2_b64 vcc, exec, s[6:7]
	s_mov_b64 s[6:7], -1
	v_cvt_pk_bf16_f32 v11, v14, v15
	global_store_dwordx4 v[12:13], v[8:11], off nt
	v_cvt_pk_bf16_f32 v4, v4, v5
	v_cvt_pk_bf16_f32 v5, v6, v7
	v_cvt_pk_bf16_f32 v6, v0, v1
	v_cvt_pk_bf16_f32 v7, v2, v3
	global_store_dwordx4 v[16:17], v[4:7], off offset:256 nt
	s_cbranch_vccnz .LBB0_155
	s_andn2_b64 vcc, exec, s[10:11]
	s_cbranch_vccnz .LBB0_154
	s_barrier
	s_branch .LBB0_154

; __device__ __forceinline__ unsigned cvt_pk_bf16(float lo, float hi) { unsigned r; asm volatile("v_cvt_pk_bf16_f32 %0, %1, %2" : "=v"(r) : "v"(lo), "v"(hi)); return r; }
; __device__ __forceinline__ float fast_sigmoid(float x) { return __builtin_amdgcn_rcpf(1.0f + __builtin_amdgcn_exp2f(-1.4426950408889634f * x)); }
;     __device__ __forceinline__ void operator()(const f32x4 (&acc)[2][2][4][2], const Unit& u, int wr, int wc, int fr, int fq) const {
;     ...
;         for (int ai = 0; ai < 2; ++ai)
; #pragma unroll
;             for (int m = 0; m < 4; ++m) { bf16_t* rowp = O + (size_t)(row0 + ai * HALF + m * 16) * ldc + col0;
;                 float v[8];
; #pragma unroll
;                 for (int n = 0; n < 2; ++n)
; #pragma unroll
;                     for (int i = 0; i < 4; ++i) { const float g = acc[ai][0][m][n][i], up = acc[ai][1][m][n][i]; v[n * 4 + i] = g * fast_sigmoid(g) * up; }
;                 u32x4 w; w.x = cvt_pk_bf16(v[0], v[1]); w.y = cvt_pk_bf16(v[2], v[3]); w.z = cvt_pk_bf16(v[4], v[5]); w.w = cvt_pk_bf16(v[6], v[7]);
;                 *(u32x4*)rowp = w; }
.LBB0_526:
	v_mul_f32_e32 v148, 0xbfb8aa3b, v124
	v_exp_f32_e32 v155, v148
	v_mul_f32_e32 v148, 0xbfb8aa3b, v125
	v_exp_f32_e32 v158, v148
	v_lshl_or_b32 v156, s75, 7, v150
	v_add_f32_e32 v155, 1.0, v155
	v_rcp_f32_e32 v155, v155
	v_add_f32_e32 v158, 1.0, v158
	v_rcp_f32_e32 v160, v158
	v_lshl_add_u32 v154, s26, 8, v137
	v_mul_f32_e32 v124, v124, v155
	v_mul_f32_e32 v116, v124, v116
	v_mul_f32_e32 v124, v125, v160
	v_mul_f32_e32 v125, 0xbfb8aa3b, v126
	v_exp_f32_e32 v125, v125
	v_mul_f32_e32 v155, 0xbfb8aa3b, v127
	v_exp_f32_e32 v155, v155
	v_mul_f32_e32 v117, v124, v117
	v_add_f32_e32 v124, 1.0, v125
	v_rcp_f32_e32 v124, v124
	v_add_f32_e32 v125, 1.0, v155
	v_mul_f32_e32 v155, 0xbfb8aa3b, v120
	v_rcp_f32_e32 v125, v125
	v_exp_f32_e32 v155, v155
	v_mul_f32_e32 v124, v126, v124
	v_mul_f32_e32 v124, v124, v118
	v_mul_f32_e32 v118, v127, v125
	v_add_f32_e32 v125, 1.0, v155
	v_rcp_f32_e32 v125, v125
	v_mul_f32_e32 v126, 0xbfb8aa3b, v121
	v_mul_f32_e32 v127, v118, v119
	v_exp_f32_e32 v126, v126
	v_mul_f32_e32 v118, v120, v125
	v_mul_f32_e32 v120, v118, v112
	v_mul_f32_e32 v118, 0xbfb8aa3b, v122
	v_exp_f32_e32 v118, v118
	v_mul_f32_e32 v119, 0xbfb8aa3b, v123
	v_exp_f32_e32 v119, v119
	v_add_f32_e32 v112, 1.0, v126
	v_rcp_f32_e32 v112, v112
	v_add_f32_e32 v118, 1.0, v118
	v_rcp_f32_e32 v118, v118
	v_add_f32_e32 v119, 1.0, v119
	v_rcp_f32_e32 v119, v119
	v_mul_f32_e32 v112, v121, v112
	v_mul_f32_e32 v121, v112, v113
	v_mul_f32_e32 v112, v122, v118
	v_ashrrev_i32_e32 v157, 31, v156
	v_mov_b64_e32 v[148:149], s[70:71]
	v_mul_f32_e32 v122, v112, v114
	v_mul_f32_e32 v112, v123, v119
	v_mad_i64_i32 v[158:159], s[28:29], v154, s74, v[148:149]
	v_mul_f32_e32 v123, v112, v115
	v_lshlrev_b64 v[112:113], 1, v[156:157]
	v_lshl_add_u64 v[118:119], v[158:159], 0, v[112:113]
	v_cvt_pk_bf16_f32 v114, v116, v117
	v_cvt_pk_bf16_f32 v115, v124, v127
	v_cvt_pk_bf16_f32 v116, v120, v121
	v_cvt_pk_bf16_f32 v117, v122, v123
	global_store_dwordx4 v[118:119], v[114:117], off nt
	s_andn2_b64 vcc, exec, s[4:5]
	s_mov_b64 s[4:5], -1
	v_mul_f32_e32 v114, 0xbfb8aa3b, v108
	v_exp_f32_e32 v114, v114
	v_mul_f32_e32 v115, 0xbfb8aa3b, v109
	v_exp_f32_e32 v115, v115
	v_or_b32_e32 v116, 16, v154
	v_add_f32_e32 v114, 1.0, v114
	v_rcp_f32_e32 v117, v114
	v_add_f32_e32 v114, 1.0, v115
	v_rcp_f32_e32 v118, v114
	v_mad_i64_i32 v[114:115], s[28:29], v116, s74, v[148:149]
	v_mul_f32_e32 v108, v108, v117
	v_mul_f32_e32 v108, v108, v100
	v_mul_f32_e32 v100, v109, v118
	v_mul_f32_e32 v109, 0xbfb8aa3b, v110
	v_exp_f32_e32 v109, v109
	v_mul_f32_e32 v116, 0xbfb8aa3b, v111
	v_exp_f32_e32 v116, v116
	v_mul_f32_e32 v117, v100, v101
	v_add_f32_e32 v100, 1.0, v109
	v_rcp_f32_e32 v100, v100
	v_add_f32_e32 v101, 1.0, v116
	v_mul_f32_e32 v109, 0xbfb8aa3b, v104
	v_rcp_f32_e32 v101, v101
	v_exp_f32_e32 v109, v109
	v_mul_f32_e32 v100, v110, v100
	v_mul_f32_e32 v102, v100, v102
	v_mul_f32_e32 v100, v111, v101
	v_add_f32_e32 v101, 1.0, v109
	v_rcp_f32_e32 v101, v101
	v_mul_f32_e32 v109, 0xbfb8aa3b, v105
	v_mul_f32_e32 v103, v100, v103
	v_exp_f32_e32 v109, v109
	v_mul_f32_e32 v100, v104, v101
	v_mul_f32_e32 v104, v100, v96
	v_mul_f32_e32 v100, 0xbfb8aa3b, v106
	v_exp_f32_e32 v100, v100
	v_mul_f32_e32 v101, 0xbfb8aa3b, v107
	v_exp_f32_e32 v101, v101
	v_add_f32_e32 v96, 1.0, v109
	v_rcp_f32_e32 v96, v96
	v_add_f32_e32 v100, 1.0, v100
	v_rcp_f32_e32 v100, v100
	v_add_f32_e32 v101, 1.0, v101
	v_rcp_f32_e32 v101, v101
	v_mul_f32_e32 v96, v105, v96
	v_mul_f32_e32 v105, v96, v97
	v_mul_f32_e32 v96, v106, v100
	v_mul_f32_e32 v106, v96, v98
	v_mul_f32_e32 v96, v107, v101
	v_mul_f32_e32 v99, v96, v99
	v_lshl_add_u64 v[100:101], v[114:115], 0, v[112:113]
	v_cvt_pk_bf16_f32 v96, v108, v117
	v_cvt_pk_bf16_f32 v97, v102, v103
	v_cvt_pk_bf16_f32 v98, v104, v105
	v_cvt_pk_bf16_f32 v99, v106, v99
	global_store_dwordx4 v[100:101], v[96:99], off nt
	s_nop 1
	v_mul_f32_e32 v96, 0xbfb8aa3b, v92
	v_exp_f32_e32 v96, v96
	v_mul_f32_e32 v97, 0xbfb8aa3b, v93
	v_exp_f32_e32 v97, v97
	v_or_b32_e32 v98, 32, v154
	v_add_f32_e32 v96, 1.0, v96
	v_rcp_f32_e32 v99, v96
	v_add_f32_e32 v96, 1.0, v97
	v_rcp_f32_e32 v100, v96
	v_mad_i64_i32 v[96:97], s[28:29], v98, s74, v[148:149]
	v_mul_f32_e32 v92, v92, v99
	v_mul_f32_e32 v92, v92, v84
	v_mul_f32_e32 v84, v93, v100
	v_mul_f32_e32 v93, 0xbfb8aa3b, v94
	v_exp_f32_e32 v93, v93
	v_mul_f32_e32 v98, 0xbfb8aa3b, v95
	v_exp_f32_e32 v98, v98
	v_mul_f32_e32 v99, v84, v85
	v_add_f32_e32 v84, 1.0, v93
	v_rcp_f32_e32 v84, v84
	v_add_f32_e32 v85, 1.0, v98
	v_mul_f32_e32 v93, 0xbfb8aa3b, v88
	v_rcp_f32_e32 v85, v85
	v_exp_f32_e32 v93, v93
	v_mul_f32_e32 v84, v94, v84
	v_mul_f32_e32 v86, v84, v86
	v_mul_f32_e32 v84, v95, v85
	v_add_f32_e32 v85, 1.0, v93
	v_rcp_f32_e32 v85, v85
	v_mul_f32_e32 v93, 0xbfb8aa3b, v89
	v_mul_f32_e32 v87, v84, v87
	v_exp_f32_e32 v93, v93
	v_mul_f32_e32 v84, v88, v85
	v_mul_f32_e32 v88, v84, v80
	v_mul_f32_e32 v84, 0xbfb8aa3b, v90
	v_exp_f32_e32 v84, v84
	v_mul_f32_e32 v85, 0xbfb8aa3b, v91
	v_exp_f32_e32 v85, v85
	v_add_f32_e32 v80, 1.0, v93
	v_rcp_f32_e32 v80, v80
	v_add_f32_e32 v84, 1.0, v84
	v_rcp_f32_e32 v84, v84
	v_add_f32_e32 v85, 1.0, v85
	v_rcp_f32_e32 v85, v85
	v_mul_f32_e32 v80, v89, v80
	v_mul_f32_e32 v89, v80, v81
	v_mul_f32_e32 v80, v90, v84
	v_mul_f32_e32 v90, v80, v82
	v_mul_f32_e32 v80, v91, v85
	v_mul_f32_e32 v83, v80, v83
	v_lshl_add_u64 v[84:85], v[96:97], 0, v[112:113]
	v_cvt_pk_bf16_f32 v80, v92, v99
	v_cvt_pk_bf16_f32 v81, v86, v87
	v_cvt_pk_bf16_f32 v82, v88, v89
	v_cvt_pk_bf16_f32 v83, v90, v83
	global_store_dwordx4 v[84:85], v[80:83], off nt
	s_nop 1
	v_mul_f32_e32 v80, 0xbfb8aa3b, v76
	v_exp_f32_e32 v80, v80
	v_mul_f32_e32 v81, 0xbfb8aa3b, v77
; __device__ __forceinline__ unsigned cvt_pk_bf16(float lo, float hi) { unsigned r; asm volatile("v_cvt_pk_bf16_f32 %0, %1, %2" : "=v"(r) : "v"(lo), "v"(hi)); return r; }
; __device__ __forceinline__ float fast_sigmoid(float x) { return __builtin_amdgcn_rcpf(1.0f + __builtin_amdgcn_exp2f(-1.4426950408889634f * x)); }
;     __device__ __forceinline__ void operator()(const f32x4 (&acc)[2][2][4][2], const Unit& u, int wr, int wc, int fr, int fq) const {
;     ...
;         for (int ai = 0; ai < 2; ++ai)
; #pragma unroll
;             for (int m = 0; m < 4; ++m) { bf16_t* rowp = O + (size_t)(row0 + ai * HALF + m * 16) * ldc + col0;
;                 float v[8];
; #pragma unroll
;                 for (int n = 0; n < 2; ++n)
; #pragma unroll
;                     for (int i = 0; i < 4; ++i) { const float g = acc[ai][0][m][n][i], up = acc[ai][1][m][n][i]; v[n * 4 + i] = g * fast_sigmoid(g) * up; }
;                 u32x4 w; w.x = cvt_pk_bf16(v[0], v[1]); w.y = cvt_pk_bf16(v[2], v[3]); w.z = cvt_pk_bf16(v[4], v[5]); w.w = cvt_pk_bf16(v[6], v[7]);
;                 *(u32x4*)rowp = w; }
	v_exp_f32_e32 v81, v81
	v_or_b32_e32 v82, 48, v154
	v_add_f32_e32 v80, 1.0, v80
	v_rcp_f32_e32 v83, v80
	v_add_f32_e32 v80, 1.0, v81
	v_rcp_f32_e32 v84, v80
	v_mad_i64_i32 v[80:81], s[28:29], v82, s74, v[148:149]
	v_mul_f32_e32 v76, v76, v83
	v_mul_f32_e32 v76, v76, v68
	v_mul_f32_e32 v68, v77, v84
	v_mul_f32_e32 v77, 0xbfb8aa3b, v78
	v_exp_f32_e32 v77, v77
	v_mul_f32_e32 v82, 0xbfb8aa3b, v79
	v_exp_f32_e32 v82, v82
	v_mul_f32_e32 v83, v68, v69
	v_add_f32_e32 v68, 1.0, v77
	v_rcp_f32_e32 v68, v68
	v_add_f32_e32 v69, 1.0, v82
	v_mul_f32_e32 v77, 0xbfb8aa3b, v72
	v_rcp_f32_e32 v69, v69
	v_exp_f32_e32 v77, v77
	v_mul_f32_e32 v68, v78, v68
	v_mul_f32_e32 v70, v68, v70
	v_mul_f32_e32 v68, v79, v69
	v_add_f32_e32 v69, 1.0, v77
	v_rcp_f32_e32 v69, v69
	v_mul_f32_e32 v77, 0xbfb8aa3b, v73
	v_mul_f32_e32 v71, v68, v71
	v_exp_f32_e32 v77, v77
	v_mul_f32_e32 v68, v72, v69
	v_mul_f32_e32 v72, v68, v64
	v_mul_f32_e32 v68, 0xbfb8aa3b, v74
	v_exp_f32_e32 v68, v68
	v_mul_f32_e32 v69, 0xbfb8aa3b, v75
	v_exp_f32_e32 v69, v69
	v_add_f32_e32 v64, 1.0, v77
	v_rcp_f32_e32 v64, v64
	v_add_f32_e32 v68, 1.0, v68
	v_rcp_f32_e32 v68, v68
	v_add_f32_e32 v69, 1.0, v69
	v_rcp_f32_e32 v69, v69
	v_mul_f32_e32 v64, v73, v64
	v_mul_f32_e32 v73, v64, v65
	v_mul_f32_e32 v64, v74, v68
	v_mul_f32_e32 v74, v64, v66
	v_mul_f32_e32 v64, v75, v69
	v_mul_f32_e32 v67, v64, v67
	v_lshl_add_u64 v[68:69], v[80:81], 0, v[112:113]
	v_cvt_pk_bf16_f32 v64, v76, v83
	v_cvt_pk_bf16_f32 v65, v70, v71
	v_cvt_pk_bf16_f32 v66, v72, v73
	v_cvt_pk_bf16_f32 v67, v74, v67
	global_store_dwordx4 v[68:69], v[64:67], off nt
	s_nop 1
	v_mul_f32_e32 v64, 0xbfb8aa3b, v60
	v_exp_f32_e32 v64, v64
	v_mul_f32_e32 v65, 0xbfb8aa3b, v61
	v_exp_f32_e32 v65, v65
	v_add_u32_e32 v66, 0x80, v154
	v_add_f32_e32 v64, 1.0, v64
	v_rcp_f32_e32 v67, v64
	v_add_f32_e32 v64, 1.0, v65
	v_rcp_f32_e32 v68, v64
	v_mad_i64_i32 v[64:65], s[28:29], v66, s74, v[148:149]
	v_mul_f32_e32 v60, v60, v67
	v_mul_f32_e32 v60, v60, v52
	v_mul_f32_e32 v52, v61, v68
	v_mul_f32_e32 v61, 0xbfb8aa3b, v62
	v_exp_f32_e32 v61, v61
	v_mul_f32_e32 v66, 0xbfb8aa3b, v63
	v_exp_f32_e32 v66, v66
	v_mul_f32_e32 v67, v52, v53
	v_add_f32_e32 v52, 1.0, v61
	v_rcp_f32_e32 v52, v52
	v_add_f32_e32 v53, 1.0, v66
	v_mul_f32_e32 v61, 0xbfb8aa3b, v56
	v_rcp_f32_e32 v53, v53
	v_exp_f32_e32 v61, v61
	v_mul_f32_e32 v52, v62, v52
	v_mul_f32_e32 v54, v52, v54
	v_mul_f32_e32 v52, v63, v53
	v_add_f32_e32 v53, 1.0, v61
	v_rcp_f32_e32 v53, v53
	v_mul_f32_e32 v61, 0xbfb8aa3b, v57
	v_mul_f32_e32 v55, v52, v55
	v_exp_f32_e32 v61, v61
	v_mul_f32_e32 v52, v56, v53
	v_mul_f32_e32 v56, v52, v48
	v_mul_f32_e32 v52, 0xbfb8aa3b, v58
	v_exp_f32_e32 v52, v52
	v_mul_f32_e32 v53, 0xbfb8aa3b, v59
	v_exp_f32_e32 v53, v53
	v_add_f32_e32 v48, 1.0, v61
	v_rcp_f32_e32 v48, v48
	v_add_f32_e32 v52, 1.0, v52
	v_rcp_f32_e32 v52, v52
	v_add_f32_e32 v53, 1.0, v53
	v_rcp_f32_e32 v53, v53
	v_mul_f32_e32 v48, v57, v48
	v_mul_f32_e32 v57, v48, v49
	v_mul_f32_e32 v48, v58, v52
	v_mul_f32_e32 v58, v48, v50
	v_mul_f32_e32 v48, v59, v53
	v_mul_f32_e32 v51, v48, v51
	v_lshl_add_u64 v[52:53], v[64:65], 0, v[112:113]
	v_cvt_pk_bf16_f32 v48, v60, v67
	v_cvt_pk_bf16_f32 v49, v54, v55
	v_cvt_pk_bf16_f32 v50, v56, v57
	v_cvt_pk_bf16_f32 v51, v58, v51
	global_store_dwordx4 v[52:53], v[48:51], off nt
	s_nop 1
	v_mul_f32_e32 v48, 0xbfb8aa3b, v44
	v_exp_f32_e32 v48, v48
	v_mul_f32_e32 v49, 0xbfb8aa3b, v45
	v_exp_f32_e32 v49, v49
	v_add_u32_e32 v50, 0x90, v154
	v_add_f32_e32 v48, 1.0, v48
	v_rcp_f32_e32 v51, v48
	v_add_f32_e32 v48, 1.0, v49
	v_rcp_f32_e32 v52, v48
	v_mad_i64_i32 v[48:49], s[28:29], v50, s74, v[148:149]
	v_mul_f32_e32 v44, v44, v51
	v_mul_f32_e32 v44, v44, v36
	v_mul_f32_e32 v36, v45, v52
	v_mul_f32_e32 v45, 0xbfb8aa3b, v46
	v_exp_f32_e32 v45, v45
	v_mul_f32_e32 v50, 0xbfb8aa3b, v47
	v_exp_f32_e32 v50, v50
	v_mul_f32_e32 v51, v36, v37
	v_add_f32_e32 v36, 1.0, v45
	v_rcp_f32_e32 v36, v36
	v_add_f32_e32 v37, 1.0, v50
	v_mul_f32_e32 v45, 0xbfb8aa3b, v40
	v_rcp_f32_e32 v37, v37
	v_exp_f32_e32 v45, v45
	v_mul_f32_e32 v36, v46, v36
	v_mul_f32_e32 v38, v36, v38
	v_mul_f32_e32 v36, v47, v37
	v_add_f32_e32 v37, 1.0, v45
	v_rcp_f32_e32 v37, v37
	v_mul_f32_e32 v45, 0xbfb8aa3b, v41
	v_mul_f32_e32 v39, v36, v39
; __device__ __forceinline__ unsigned cvt_pk_bf16(float lo, float hi) { unsigned r; asm volatile("v_cvt_pk_bf16_f32 %0, %1, %2" : "=v"(r) : "v"(lo), "v"(hi)); return r; }
; __device__ __forceinline__ float fast_sigmoid(float x) { return __builtin_amdgcn_rcpf(1.0f + __builtin_amdgcn_exp2f(-1.4426950408889634f * x)); }
; #define PG8_BAR __builtin_amdgcn_s_barrier()
;     __device__ __forceinline__ void operator()(const f32x4 (&acc)[2][2][4][2], const Unit& u, int wr, int wc, int fr, int fq) const {
;     ...
;         for (int ai = 0; ai < 2; ++ai)
; #pragma unroll
;             for (int m = 0; m < 4; ++m) { bf16_t* rowp = O + (size_t)(row0 + ai * HALF + m * 16) * ldc + col0;
;                 float v[8];
; #pragma unroll
;                 for (int n = 0; n < 2; ++n)
; #pragma unroll
;                     for (int i = 0; i < 4; ++i) { const float g = acc[ai][0][m][n][i], up = acc[ai][1][m][n][i]; v[n * 4 + i] = g * fast_sigmoid(g) * up; }
;                 u32x4 w; w.x = cvt_pk_bf16(v[0], v[1]); w.y = cvt_pk_bf16(v[2], v[3]); w.z = cvt_pk_bf16(v[4], v[5]); w.w = cvt_pk_bf16(v[6], v[7]);
;                 *(u32x4*)rowp = w; }
; template <class Epi, class Sched, bool ALIGN_EPI = false, bool SP2 = false>
; __device__ __forceinline__ void gemm_phase(PG8_LAS unsigned char* lds, const Gemm g, const Sched& S, const Epi& E) {
;     ...
;         if constexpr (ALIGN_EPI) { if (wr == 0) PG8_BAR; }
;         if constexpr (!Epi::AFTER_DRAIN) { E(acc, cur, wr, wc, fr, fq); S.done(cur); }
;         if (!has_next) break;
; #pragma unroll
;         for (int a = 0; a < 2; ++a)
; #pragma unroll
;             for (int b = 0; b < 2; ++b)
; #pragma unroll
;                 for (int m = 0; m < 4; ++m)
; #pragma unroll
;                     for (int n = 0; n < 2; ++n) acc[a][b][m][n] = (f32x4){0.f, 0.f, 0.f, 0.f};
;         cur = nxt; cA = nA; cB = nB; ++ui;
;         if constexpr (ALIGN_EPI) { if (wr == 1) PG8_BAR; }
	v_exp_f32_e32 v45, v45
	v_mul_f32_e32 v36, v40, v37
	v_mul_f32_e32 v40, v36, v32
	v_mul_f32_e32 v36, 0xbfb8aa3b, v42
	v_exp_f32_e32 v36, v36
	v_mul_f32_e32 v37, 0xbfb8aa3b, v43
	v_exp_f32_e32 v37, v37
	v_add_f32_e32 v32, 1.0, v45
	v_rcp_f32_e32 v32, v32
	v_add_f32_e32 v36, 1.0, v36
	v_rcp_f32_e32 v36, v36
	v_add_f32_e32 v37, 1.0, v37
	v_rcp_f32_e32 v37, v37
	v_mul_f32_e32 v32, v41, v32
	v_mul_f32_e32 v41, v32, v33
	v_mul_f32_e32 v32, v42, v36
	v_mul_f32_e32 v42, v32, v34
	v_mul_f32_e32 v32, v43, v37
	v_mul_f32_e32 v35, v32, v35
	v_lshl_add_u64 v[36:37], v[48:49], 0, v[112:113]
	v_cvt_pk_bf16_f32 v32, v44, v51
	v_cvt_pk_bf16_f32 v33, v38, v39
	v_cvt_pk_bf16_f32 v34, v40, v41
	v_cvt_pk_bf16_f32 v35, v42, v35
	global_store_dwordx4 v[36:37], v[32:35], off nt
	s_nop 1
	v_mul_f32_e32 v32, 0xbfb8aa3b, v28
	v_exp_f32_e32 v32, v32
	v_mul_f32_e32 v33, 0xbfb8aa3b, v29
	v_exp_f32_e32 v33, v33
	v_add_u32_e32 v34, 0xa0, v154
	v_add_f32_e32 v32, 1.0, v32
	v_rcp_f32_e32 v35, v32
	v_add_f32_e32 v32, 1.0, v33
	v_rcp_f32_e32 v36, v32
	v_mad_i64_i32 v[32:33], s[28:29], v34, s74, v[148:149]
	v_mul_f32_e32 v28, v28, v35
	v_mul_f32_e32 v28, v28, v20
	v_mul_f32_e32 v20, v29, v36
	v_mul_f32_e32 v29, 0xbfb8aa3b, v30
	v_exp_f32_e32 v29, v29
	v_mul_f32_e32 v34, 0xbfb8aa3b, v31
	v_exp_f32_e32 v34, v34
	v_mul_f32_e32 v35, v20, v21
	v_add_f32_e32 v20, 1.0, v29
	v_rcp_f32_e32 v20, v20
	v_add_f32_e32 v21, 1.0, v34
	v_mul_f32_e32 v29, 0xbfb8aa3b, v24
	v_rcp_f32_e32 v21, v21
	v_exp_f32_e32 v29, v29
	v_mul_f32_e32 v20, v30, v20
	v_mul_f32_e32 v22, v20, v22
	v_mul_f32_e32 v20, v31, v21
	v_add_f32_e32 v21, 1.0, v29
	v_rcp_f32_e32 v21, v21
	v_mul_f32_e32 v29, 0xbfb8aa3b, v25
	v_mul_f32_e32 v23, v20, v23
	v_exp_f32_e32 v29, v29
	v_mul_f32_e32 v20, v24, v21
	v_mul_f32_e32 v24, v20, v16
	v_mul_f32_e32 v20, 0xbfb8aa3b, v26
	v_exp_f32_e32 v20, v20
	v_mul_f32_e32 v21, 0xbfb8aa3b, v27
	v_exp_f32_e32 v21, v21
	v_add_f32_e32 v16, 1.0, v29
	v_rcp_f32_e32 v16, v16
	v_add_f32_e32 v20, 1.0, v20
	v_rcp_f32_e32 v20, v20
	v_add_f32_e32 v21, 1.0, v21
	v_rcp_f32_e32 v21, v21
	v_mul_f32_e32 v16, v25, v16
	v_mul_f32_e32 v25, v16, v17
	v_mul_f32_e32 v16, v26, v20
	v_mul_f32_e32 v26, v16, v18
	v_mul_f32_e32 v16, v27, v21
	v_mul_f32_e32 v19, v16, v19
	v_lshl_add_u64 v[20:21], v[32:33], 0, v[112:113]
	v_cvt_pk_bf16_f32 v16, v28, v35
	v_cvt_pk_bf16_f32 v17, v22, v23
	v_cvt_pk_bf16_f32 v18, v24, v25
	v_cvt_pk_bf16_f32 v19, v26, v19
	global_store_dwordx4 v[20:21], v[16:19], off nt
	s_nop 1
	v_mul_f32_e32 v16, 0xbfb8aa3b, v12
	v_exp_f32_e32 v16, v16
	v_mul_f32_e32 v17, 0xbfb8aa3b, v13
	v_exp_f32_e32 v17, v17
	v_add_u32_e32 v18, 0xb0, v154
	v_add_f32_e32 v16, 1.0, v16
	v_rcp_f32_e32 v19, v16
	v_add_f32_e32 v16, 1.0, v17
	v_rcp_f32_e32 v20, v16
	v_mad_i64_i32 v[16:17], s[28:29], v18, s74, v[148:149]
	v_mul_f32_e32 v12, v12, v19
	v_mul_f32_e32 v12, v12, v4
	v_mul_f32_e32 v4, v13, v20
	v_mul_f32_e32 v13, 0xbfb8aa3b, v14
	v_exp_f32_e32 v13, v13
	v_mul_f32_e32 v18, 0xbfb8aa3b, v15
	v_exp_f32_e32 v18, v18
	v_mul_f32_e32 v19, v4, v5
	v_add_f32_e32 v4, 1.0, v13
	v_rcp_f32_e32 v4, v4
	v_add_f32_e32 v5, 1.0, v18
	v_mul_f32_e32 v13, 0xbfb8aa3b, v8
	v_rcp_f32_e32 v5, v5
	v_exp_f32_e32 v13, v13
	v_mul_f32_e32 v4, v14, v4
	v_mul_f32_e32 v6, v4, v6
	v_mul_f32_e32 v4, v15, v5
	v_add_f32_e32 v5, 1.0, v13
	v_rcp_f32_e32 v5, v5
	v_mul_f32_e32 v13, 0xbfb8aa3b, v9
	v_mul_f32_e32 v7, v4, v7
	v_exp_f32_e32 v13, v13
	v_mul_f32_e32 v4, v8, v5
	v_mul_f32_e32 v8, v4, v0
	v_mul_f32_e32 v4, 0xbfb8aa3b, v10
	v_exp_f32_e32 v4, v4
	v_mul_f32_e32 v5, 0xbfb8aa3b, v11
	v_exp_f32_e32 v5, v5
	v_add_f32_e32 v0, 1.0, v13
	v_rcp_f32_e32 v0, v0
	v_add_f32_e32 v4, 1.0, v4
	v_rcp_f32_e32 v4, v4
	v_add_f32_e32 v5, 1.0, v5
	v_rcp_f32_e32 v5, v5
	v_mul_f32_e32 v0, v9, v0
	v_mul_f32_e32 v9, v0, v1
	v_mul_f32_e32 v0, v10, v4
	v_mul_f32_e32 v10, v0, v2
	v_mul_f32_e32 v0, v11, v5
	v_mul_f32_e32 v3, v0, v3
	v_lshl_add_u64 v[4:5], v[16:17], 0, v[112:113]
	v_cvt_pk_bf16_f32 v0, v12, v19
	v_cvt_pk_bf16_f32 v1, v6, v7
	v_cvt_pk_bf16_f32 v2, v8, v9
	v_cvt_pk_bf16_f32 v3, v10, v3
	global_store_dwordx4 v[4:5], v[0:3], off nt
	s_cbranch_vccnz .LBB0_519
	s_andn2_b64 vcc, exec, s[12:13]
	s_cbranch_vccnz .LBB0_518
	s_barrier
	s_branch .LBB0_518
